# GQA loop: waves 4-7 run exp/PV one tile behind QK (V triple-buffered), QK section at setprio 1, exp/PV at setprio 0
# baseline (speedup 1.0000x reference)
; #define LOADKV(t) do { \
;     _Pragma("unroll") for (int j = 0; j < NKC; ++j) if (j + 1 < NKC || k1) rk[j] = *(const u32x4*)(kh + (size_t)(t) * 64 * DQK + (size_t)(tid + 512 * j) * 8); \
;     _Pragma("unroll") for (int j = 0; j < NVC; ++j) rv[j] = *(const u32x4*)(vg0 + (size_t)(64 * j) * S + (size_t)(t) * 64); } while (0)
; #pragma unroll
;   for (int sl = 0; sl < 8; ++sl) m = max(m, kmx[sl * 64 + idx]);
;   return sqrtf(__uint_as_float(m)); }
; template <int DQK, int DV>
; __device__ __forceinline__ void attn_pass2(const bf16_t* __restrict__ qh, const bf16_t* __restrict__ kh, const bf16_t* __restrict__ vth, int q0, char* smem, f32x16 (&o)[2][DV / 32], float kmax, int wvp) {
;     ...
;   bf16x8 qf[2][NKS];
; #pragma unroll
;   for (int qb = 0; qb < 2; ++qb) {
;     const bf16_t* qrow = qh + (size_t)(q0 + 64 * wid + 32 * qb + r) * DQK + 8 * h;
; #pragma unroll
;     for (int ks = 0; ks < NKS; ++ks) qf[qb][ks] = *(const bf16x8*)(qrow + 16 * ks);
;   }
;   int klo[NKC], vlo[NVC];
;   const bf16_t* vg0 = vth + (size_t)(tid >> 3) * S + (tid & 7) * 8;
; #pragma unroll
;   for (int j = 0; j < NKC; ++j) { const int c = tid + 512 * j; klo[j] = (c / CK) * KP + (c % CK) * 16; }
; #pragma unroll
;   for (int j = 0; j < NVC; ++j) { const int c = tid + 512 * j; vlo[j] = (c >> 3) * VP + (c & 7) * 16; }
;   u32x4 rk[NKC], rv[NVC];
;   const bool k1 = (TKC % 512 == 0) || (tid < TKC % 512);
;     ...
;   LOADKV(0);
; #pragma unroll
;   for (int qb = 0; qb < 2; ++qb)
; #pragma unroll
;     for (int eb = 0; eb < NEB; ++eb)
; #pragma unroll
;       for (int i = 0; i < 16; ++i) o[qb][eb][i] = 0.f;
;   float l_run[2] = {0.f, 0.f}, mref[2];
; #pragma unroll
;   for (int qb = 0; qb < 2; ++qb) {
;     float qq = 0.f;
; #pragma unroll
;     for (int ks = 0; ks < NKS; ++ks)
; #pragma unroll
;       for (int j = 0; j < 8; ++j) { const float t = bf2f((unsigned short)qf[qb][ks][j]); qq += t * t; }
;     { auto rr = __builtin_amdgcn_permlane32_swap(__float_as_uint(qq), __float_as_uint(qq), false, false); qq = __uint_as_float(rr[0]) + __uint_as_float(rr[1]); }
;     mref[qb] = sqrtf(qq) * kmax * 1.01f + 0.01f;
;   }
.LBB0_1427:
	s_cmpk_gt_i32 s75, 0xff
	s_mov_b64 s[6:7], -1
	s_cbranch_scc0 .LBB0_1434
	s_bfe_u32 s11, s75, 0x10003
	s_lshl_b32 s7, s74, 18
	s_lshl_b32 s6, s11, 21
	s_and_b32 s7, s7, 0x100000
	s_or_b32 s13, s6, s7
	s_lshl_b32 s7, s75, 20
	s_and_b32 s10, s75, 7
	s_bfe_u32 s6, s75, 0x10002
	s_and_b32 s7, s7, 0xf00000
	v_readlane_b32 s8, v252, 14
	s_add_u32 s14, s8, s7
	v_readlane_b32 s7, v252, 16
	s_addc_u32 s15, s7, 0
	s_lshl_b32 s7, s11, 1
	s_or_b32 s16, s7, s6
	s_lshl_b32 s6, s16, 20
	v_readlane_b32 s7, v252, 4
	s_add_u32 s8, s7, s6
	v_readlane_b32 s7, v252, 6
	s_addc_u32 s9, s7, 0
	v_readlane_b32 s18, v252, 17
	v_readlane_b32 s19, v252, 18
	s_add_u32 s6, s18, s6
	s_addc_u32 s7, s19, 0
	s_lshl_b32 s16, s16, 2
	s_lshl_b32 s12, s75, 5
	v_mov_b32_e32 v0, s16
	s_and_b32 s12, s12, 0x7ffffe00
	global_load_dword v20, v0, s[46:47] offset:128
	global_load_dword v21, v0, s[46:47] offset:384
	global_load_dword v22, v0, s[46:47] offset:640
	global_load_dword v23, v0, s[46:47] offset:896
	global_load_dword v24, v0, s[46:47] offset:1152
	global_load_dword v25, v0, s[46:47] offset:1408
	global_load_dword v26, v0, s[46:47] offset:1664
	global_load_dword v27, v0, s[46:47] offset:1920
	v_mbcnt_lo_u32_b32 v0, -1, 0
	v_mbcnt_hi_u32_b32 v0, -1, v0
	s_addk_i32 s12, 0xe000
	v_add_u32_e32 v2, s27, v0
	v_mov_b32_e32 v9, v191
	v_and_b32_e32 v0, 0xffffffc0, v2
	v_and_b32_e32 v28, 31, v2
	v_add_u32_e32 v0, s12, v0
	v_or_b32_e32 v12, v0, v28
	v_lshrrev_b32_e32 v29, 1, v2
	v_and_b32_e32 v190, 16, v29
	v_ashrrev_i32_e32 v13, 31, v12
	v_lshl_add_u64 v[14:15], s[14:15], 0, v[190:191]
	v_lshlrev_b64 v[0:1], 7, v[12:13]
	v_lshl_add_u64 v[16:17], v[14:15], 0, v[0:1]
	global_load_dwordx4 v[128:131], v[16:17], off
	global_load_dwordx4 v[132:135], v[16:17], off offset:32
	global_load_dwordx4 v[136:139], v[16:17], off offset:64
	global_load_dwordx4 v[140:143], v[16:17], off offset:96
	v_or_b32_e32 v18, 32, v12
	v_ashrrev_i32_e32 v19, 31, v18
	v_lshlrev_b64 v[16:17], 7, v[18:19]
	v_lshl_add_u64 v[14:15], v[14:15], 0, v[16:17]
	global_load_dwordx4 v[144:147], v[14:15], off
	global_load_dwordx4 v[148:151], v[14:15], off offset:32
	global_load_dwordx4 v[152:155], v[14:15], off offset:64
	global_load_dwordx4 v[156:159], v[14:15], off offset:96
	v_ashrrev_i32_e32 v10, 3, v2
	v_ashrrev_i32_e32 v11, 31, v10
	v_lshlrev_b32_e32 v1, 4, v2
	v_lshlrev_b64 v[4:5], 14, v[10:11]
	v_and_b32_e32 v8, 0x70, v1
	v_lshl_add_u64 v[12:13], s[6:7], 0, v[4:5]
	v_lshl_add_u64 v[12:13], v[12:13], 0, v[8:9]
	v_ashrrev_i32_e32 v3, 31, v2
	v_lshlrev_b64 v[6:7], 4, v[2:3]
	v_lshrrev_b32_e32 v1, 29, v3
	v_add_u32_e32 v1, v2, v1
	v_lshrrev_b32_e32 v3, 3, v1
	v_and_b32_e32 v1, 0xffffff8, v1
	v_mul_lo_u32 v3, v3, s37
	v_sub_u32_e32 v1, v2, v1
	s_waitcnt vmcnt(32)
	v_lshl_add_u32 v184, v1, 4, v3
	v_lshlrev_b32_e32 v3, 1, v2
	v_and_b32_e32 v1, 19, v2
	v_and_b32_e32 v3, 8, v3
	v_mov_b32_e32 v0, 0
	v_mad_u32_u24 v185, v28, s37, v190
	v_mov_b32_e32 v28, v0
	v_mov_b32_e32 v30, v0
	v_mov_b32_e32 v31, v0
	v_mov_b32_e32 v32, v0
	v_mov_b32_e32 v33, v0
	v_mov_b32_e32 v34, v0
	v_mov_b32_e32 v35, v0
	v_mov_b32_e32 v36, v0
	v_mov_b32_e32 v37, v0
	v_mov_b32_e32 v38, v0
	v_mov_b32_e32 v39, v0
	v_mov_b32_e32 v40, v0
	v_mov_b32_e32 v41, v0
	v_mov_b32_e32 v42, v0
	v_mov_b32_e32 v43, v0
	v_mov_b32_e32 v44, v0
	v_mov_b32_e32 v45, v0
	v_mov_b32_e32 v46, v0
	v_mov_b32_e32 v47, v0
	v_mov_b32_e32 v48, v0
	v_mov_b32_e32 v49, v0
	v_mov_b32_e32 v50, v0
	v_mov_b32_e32 v51, v0
	v_mov_b32_e32 v52, v0
	v_mov_b32_e32 v53, v0
	v_mov_b32_e32 v54, v0
	v_mov_b32_e32 v55, v0
	v_mov_b32_e32 v56, v0
	v_mov_b32_e32 v57, v0
	v_mov_b32_e32 v58, v0
	s_waitcnt vmcnt(14)
	v_max_u32_e32 v9, v20, v21
	v_mov_b32_e32 v59, v0
	s_waitcnt vmcnt(12)
	v_max3_u32 v9, v9, v22, v23
	v_mov_b32_e32 v60, v0
	s_waitcnt vmcnt(10)
	v_max3_u32 v9, v9, v24, v25
	v_mov_b32_e32 v61, v0
	s_waitcnt vmcnt(8)
	v_max3_u32 v9, v9, v26, v27
	v_mul_f32_e32 v11, 0x4f800000, v9
	v_cmp_gt_f32_e32 vcc, s36, v9
	v_mov_b32_e32 v27, v0
	v_mov_b32_e32 v62, v0
	v_cndmask_b32_e32 v9, v9, v11, vcc
	v_sqrt_f32_e32 v11, v9
	v_mov_b32_e32 v63, v0
	v_mov_b32_e32 v174, v0
	v_mov_b32_e32 v175, v0
	v_add_u32_e32 v23, -1, v11
	v_add_u32_e32 v24, 1, v11
	v_fma_f32 v25, -v23, v11, v9
	v_fma_f32 v26, -v24, v11, v9
	s_waitcnt vmcnt(7)
	v_and_b32_e32 v15, 0xffff0000, v128
	v_lshlrev_b32_e32 v14, 16, v128
	v_mul_f32_e32 v15, v15, v15
	v_lshlrev_b32_e32 v16, 16, v129
	v_fmac_f32_e32 v15, v14, v14
	v_and_b32_e32 v17, 0xffff0000, v129
	v_fmac_f32_e32 v15, v16, v16
	v_lshlrev_b32_e32 v18, 16, v130
	v_cmp_ge_f32_e64 s[6:7], 0, v25
	v_fmac_f32_e32 v15, v17, v17
	v_and_b32_e32 v19, 0xffff0000, v130
	v_cndmask_b32_e64 v11, v11, v23, s[6:7]
	v_cmp_lt_f32_e64 s[6:7], 0, v26
	v_fmac_f32_e32 v15, v18, v18
	v_lshlrev_b32_e32 v20, 16, v131
	v_cndmask_b32_e64 v11, v11, v24, s[6:7]
	v_fmac_f32_e32 v15, v19, v19
	v_and_b32_e32 v21, 0xffff0000, v131
	v_mul_f32_e32 v14, 0x37800000, v11
	v_fmac_f32_e32 v15, v20, v20
	s_waitcnt vmcnt(6)
	v_lshlrev_b32_e32 v22, 16, v132
	v_cndmask_b32_e32 v11, v11, v14, vcc
	v_cmp_class_f32_e32 vcc, v9, v210
	v_fmac_f32_e32 v15, v21, v21
	v_fmac_f32_e32 v15, v22, v22
	v_cndmask_b32_e32 v9, v11, v9, vcc
	v_and_b32_e32 v11, 0xffff0000, v132
	v_fmac_f32_e32 v15, v11, v11
	v_lshlrev_b32_e32 v11, 16, v133
	v_fmac_f32_e32 v15, v11, v11
	v_and_b32_e32 v11, 0xffff0000, v133
	v_fmac_f32_e32 v15, v11, v11
	v_lshlrev_b32_e32 v11, 16, v134
	v_fmac_f32_e32 v15, v11, v11
	v_and_b32_e32 v11, 0xffff0000, v134
	v_fmac_f32_e32 v15, v11, v11
	v_lshlrev_b32_e32 v11, 16, v135
	v_fmac_f32_e32 v15, v11, v11
	v_and_b32_e32 v11, 0xffff0000, v135
	v_fmac_f32_e32 v15, v11, v11
	s_waitcnt vmcnt(5)
; __device__ __forceinline__ int swz23(int r) { return (r & ~12) | ((r & 4) << 1) | ((r & 8) >> 1); }
; #define LOADKV(t) do { \
;     _Pragma("unroll") for (int j = 0; j < NKC; ++j) if (j + 1 < NKC || k1) rk[j] = *(const u32x4*)(kh + (size_t)(t) * 64 * DQK + (size_t)(tid + 512 * j) * 8); \
;     _Pragma("unroll") for (int j = 0; j < NVC; ++j) rv[j] = *(const u32x4*)(vg0 + (size_t)(64 * j) * S + (size_t)(t) * 64); } while (0)
; #define STOREKV(slot) do { \
;     _Pragma("unroll") for (int j = 0; j < NKC; ++j) if (j + 1 < NKC || k1) *(u32x4*)(sK + (slot) * KSB + klo[j]) = rk[j]; \
;     _Pragma("unroll") for (int j = 0; j < NVC; ++j) *(u32x4*)(sV + (slot) * VSB + vlo[j]) = rv[j]; } while (0)
; #define STOREKV(slot) do { int tl_ = TIDV(); asm volatile("" : "+v"(tl_)); const int klo = KLO(tl_), vlo0 = VLO(tl_), vlo1 = vlo0 + 64 * VP; *(u32x4*)(sK + ((slot) * 2) * KSB + klo) = rk[0]; *(u32x4*)(sK + ((slot) * 2 + 1) * KSB + klo) = rk[1]; \
;     *(u32x4*)(sV + (slot) * VSB + vlo0) = rv[0]; *(u32x4*)(sV + (slot) * VSB + vlo1) = rv[1]; } while (0)
; template <int DQK, int DV>
; __device__ __forceinline__ void attn_pass2(const bf16_t* __restrict__ qh, const bf16_t* __restrict__ kh, const bf16_t* __restrict__ vth, int q0, char* smem, f32x16 (&o)[2][DV / 32], float kmax, int wvp) {
;     ...
;   float l_run[2] = {0.f, 0.f}, mref[2];
; #pragma unroll
;   for (int qb = 0; qb < 2; ++qb) {
;     float qq = 0.f;
; #pragma unroll
;     for (int ks = 0; ks < NKS; ++ks)
; #pragma unroll
;       for (int j = 0; j < 8; ++j) { const float t = bf2f((unsigned short)qf[qb][ks][j]); qq += t * t; }
;     { auto rr = __builtin_amdgcn_permlane32_swap(__float_as_uint(qq), __float_as_uint(qq), false, false); qq = __uint_as_float(rr[0]) + __uint_as_float(rr[1]); }
;     mref[qb] = sqrtf(qq) * kmax * 1.01f + 0.01f;
;   }
;   __syncthreads();
;   STOREKV(0);
;   LOADKV(1);
;   const int kofs = swz23(r) * KP + 16 * h, vofs = r * VP + 16 * h;
; #pragma unroll
;   for (int qb = 0; qb < 2; ++qb)
; #pragma unroll
;     for (int ks = 0; ks < NKS; ++ks) asm volatile("" :: "v"(qf[qb][ks]));
	v_lshlrev_b32_e32 v11, 16, v136
	v_fmac_f32_e32 v15, v11, v11
	v_and_b32_e32 v11, 0xffff0000, v136
	v_fmac_f32_e32 v15, v11, v11
	v_lshlrev_b32_e32 v11, 16, v137
	v_fmac_f32_e32 v15, v11, v11
	v_and_b32_e32 v11, 0xffff0000, v137
	v_fmac_f32_e32 v15, v11, v11
	v_lshlrev_b32_e32 v11, 16, v138
	v_fmac_f32_e32 v15, v11, v11
	v_and_b32_e32 v11, 0xffff0000, v138
	v_fmac_f32_e32 v15, v11, v11
	v_lshlrev_b32_e32 v11, 16, v139
	v_fmac_f32_e32 v15, v11, v11
	v_and_b32_e32 v11, 0xffff0000, v139
	v_fmac_f32_e32 v15, v11, v11
	s_waitcnt vmcnt(4)
	v_lshlrev_b32_e32 v11, 16, v140
	v_fmac_f32_e32 v15, v11, v11
	v_and_b32_e32 v11, 0xffff0000, v140
	v_fmac_f32_e32 v15, v11, v11
	v_lshlrev_b32_e32 v11, 16, v141
	v_fmac_f32_e32 v15, v11, v11
	v_and_b32_e32 v11, 0xffff0000, v141
	v_fmac_f32_e32 v15, v11, v11
	v_lshlrev_b32_e32 v11, 16, v142
	v_fmac_f32_e32 v15, v11, v11
	v_and_b32_e32 v11, 0xffff0000, v142
	v_fmac_f32_e32 v15, v11, v11
	v_lshlrev_b32_e32 v11, 16, v143
	v_fmac_f32_e32 v15, v11, v11
	v_and_b32_e32 v11, 0xffff0000, v143
	v_fmac_f32_e32 v15, v11, v11
	v_mov_b32_e32 v11, v15
	s_nop 1
	v_permlane32_swap_b32_e32 v15, v11
	v_add_f32_e32 v11, v15, v11
	v_mul_f32_e32 v14, 0x4f800000, v11
	v_cmp_gt_f32_e32 vcc, s36, v11
	v_lshl_add_u64 v[22:23], s[8:9], 0, v[6:7]
	s_add_u32 s8, s0, s13
	v_cndmask_b32_e32 v11, v11, v14, vcc
	global_load_dwordx4 v[14:17], v[22:23], off
	global_load_dwordx4 v[18:21], v[12:13], off
	v_sqrt_f32_e32 v24, v11
	s_barrier
	v_add_u32_e32 v25, -1, v24
	v_fma_f32 v26, -v25, v24, v11
	v_cmp_ge_f32_e64 s[6:7], 0, v26
	v_add_u32_e32 v26, 1, v24
	s_addc_u32 s9, s1, 0
	v_cndmask_b32_e64 v25, v24, v25, s[6:7]
	v_fma_f32 v24, -v26, v24, v11
	v_cmp_lt_f32_e64 s[6:7], 0, v24
	v_lshl_add_u64 v[170:171], s[8:9], 0, v[6:7]
	s_add_u32 s8, s2, s13
	v_cndmask_b32_e64 v24, v25, v26, s[6:7]
	v_mul_f32_e32 v25, 0x37800000, v24
	s_waitcnt vmcnt(5)
	v_and_b32_e32 v26, 0xffff0000, v144
	v_cndmask_b32_e32 v24, v24, v25, vcc
	v_lshlrev_b32_e32 v25, 16, v144
	v_mul_f32_e32 v26, v26, v26
	v_fmac_f32_e32 v26, v25, v25
	v_lshlrev_b32_e32 v25, 16, v145
	v_fmac_f32_e32 v26, v25, v25
	v_and_b32_e32 v25, 0xffff0000, v145
	v_fmac_f32_e32 v26, v25, v25
	v_lshlrev_b32_e32 v25, 16, v146
	v_fmac_f32_e32 v26, v25, v25
	v_and_b32_e32 v25, 0xffff0000, v146
	v_fmac_f32_e32 v26, v25, v25
	v_lshlrev_b32_e32 v25, 16, v147
	v_fmac_f32_e32 v26, v25, v25
	v_and_b32_e32 v25, 0xffff0000, v147
	v_fmac_f32_e32 v26, v25, v25
	s_waitcnt vmcnt(4)
	v_lshlrev_b32_e32 v25, 16, v148
	v_fmac_f32_e32 v26, v25, v25
	v_and_b32_e32 v25, 0xffff0000, v148
	v_fmac_f32_e32 v26, v25, v25
	v_lshlrev_b32_e32 v25, 16, v149
	v_fmac_f32_e32 v26, v25, v25
	v_and_b32_e32 v25, 0xffff0000, v149
	v_fmac_f32_e32 v26, v25, v25
	v_lshlrev_b32_e32 v25, 16, v150
	v_fmac_f32_e32 v26, v25, v25
	v_and_b32_e32 v25, 0xffff0000, v150
	v_fmac_f32_e32 v26, v25, v25
	v_lshlrev_b32_e32 v25, 16, v151
	v_fmac_f32_e32 v26, v25, v25
	v_and_b32_e32 v25, 0xffff0000, v151
	v_fmac_f32_e32 v26, v25, v25
	s_waitcnt vmcnt(3)
	v_lshlrev_b32_e32 v25, 16, v152
	v_fmac_f32_e32 v26, v25, v25
	v_and_b32_e32 v25, 0xffff0000, v152
	v_fmac_f32_e32 v26, v25, v25
	v_lshlrev_b32_e32 v25, 16, v153
	v_fmac_f32_e32 v26, v25, v25
	v_and_b32_e32 v25, 0xffff0000, v153
	v_fmac_f32_e32 v26, v25, v25
	v_lshlrev_b32_e32 v25, 16, v154
	v_fmac_f32_e32 v26, v25, v25
	v_and_b32_e32 v25, 0xffff0000, v154
	v_fmac_f32_e32 v26, v25, v25
	v_lshlrev_b32_e32 v25, 16, v155
	v_fmac_f32_e32 v26, v25, v25
	v_and_b32_e32 v25, 0xffff0000, v155
	v_fmac_f32_e32 v26, v25, v25
	s_waitcnt vmcnt(2)
	v_lshlrev_b32_e32 v25, 16, v156
	v_fmac_f32_e32 v26, v25, v25
	v_and_b32_e32 v25, 0xffff0000, v156
	v_fmac_f32_e32 v26, v25, v25
	v_lshlrev_b32_e32 v25, 16, v157
	v_fmac_f32_e32 v26, v25, v25
	v_and_b32_e32 v25, 0xffff0000, v157
	v_fmac_f32_e32 v26, v25, v25
	v_lshlrev_b32_e32 v25, 16, v158
	v_fmac_f32_e32 v26, v25, v25
	v_and_b32_e32 v25, 0xffff0000, v158
	v_fmac_f32_e32 v26, v25, v25
	v_lshlrev_b32_e32 v25, 16, v159
	v_fmac_f32_e32 v26, v25, v25
	v_and_b32_e32 v25, 0xffff0000, v159
	v_fmac_f32_e32 v26, v25, v25
	v_mov_b32_e32 v25, v26
	s_nop 1
	v_permlane32_swap_b32_e32 v26, v25
	v_add_f32_e32 v25, v26, v25
	v_mul_f32_e32 v26, 0x4f800000, v25
	v_cmp_gt_f32_e32 vcc, s36, v25
	v_cmp_class_f32_e64 s[6:7], v11, v210
	s_waitcnt vmcnt(1)
	ds_write_b128 v184, v[14:17]
	v_cndmask_b32_e32 v25, v25, v26, vcc
	v_sqrt_f32_e32 v26, v25
	v_cndmask_b32_e64 v11, v24, v11, s[6:7]
	v_mul_f32_e32 v11, v9, v11
	v_fmamk_f32 v182, v11, 0x3f8147ae, v211
	v_add_u32_e32 v11, -1, v26
	v_fma_f32 v24, -v11, v26, v25
	v_cmp_ge_f32_e64 s[6:7], 0, v24
	v_add_u32_e32 v24, 1, v26
	s_addc_u32 s9, s3, 0
	v_cndmask_b32_e64 v11, v26, v11, s[6:7]
	v_fma_f32 v26, -v24, v26, v25
	v_cmp_lt_f32_e64 s[6:7], 0, v26
	v_mov_b32_e32 v6, v0
	v_mov_b32_e32 v7, v0
	v_cndmask_b32_e64 v11, v11, v24, s[6:7]
	v_mul_f32_e32 v24, 0x37800000, v11
	v_cndmask_b32_e32 v11, v11, v24, vcc
	v_cmp_class_f32_e32 vcc, v25, v210
	v_mov_b32_e32 v14, v0
	v_mov_b32_e32 v15, v0
	v_cndmask_b32_e32 v11, v11, v25, vcc
	v_mul_f32_e32 v9, v9, v11
	v_mad_u64_u32 v[168:169], s[6:7], v10, s37, v[8:9]
	v_add_co_u32_e32 v8, vcc, s68, v22
	v_fmamk_f32 v183, v9, 0x3f8147ae, v211
	s_waitcnt vmcnt(0)
	ds_write_b128 v168, v[18:21] offset:18432
	v_addc_co_u32_e32 v9, vcc, 0, v23, vcc
	global_load_dwordx4 v[160:163], v[8:9], off
	global_load_dwordx4 v[164:167], v[12:13], off offset:128
	v_and_b32_e32 v8, 4, v29
	v_or3_b32 v1, v1, v3, v8
	v_mad_u32_u24 v169, v1, s37, v190
	v_and_b32_e32 v1, 7, v2
	v_lshl_or_b32 v4, v1, 4, v4
	s_mov_b32 s6, 0
	v_lshl_add_u64 v[172:173], s[8:9], 0, v[4:5]
	v_mov_b32_e32 v1, v0
	v_mov_b32_e32 v2, v0
	v_mov_b32_e32 v3, v0
	v_mov_b32_e32 v4, v0
	v_mov_b32_e32 v5, v0
	v_mov_b32_e32 v8, v0
	v_mov_b32_e32 v9, v0
	v_mov_b32_e32 v10, v0
	v_mov_b32_e32 v11, v0
	v_mov_b32_e32 v12, v0
	v_mov_b32_e32 v13, v0
	v_mov_b32_e32 v16, v0
	v_mov_b32_e32 v17, v0
	v_mov_b32_e32 v18, v0
	v_mov_b32_e32 v19, v0
	v_mov_b32_e32 v20, v0
	v_mov_b32_e32 v21, v0
	v_mov_b32_e32 v22, v0
	v_mov_b32_e32 v23, v0
	v_mov_b32_e32 v24, v0
	v_mov_b32_e32 v25, v0
	v_mov_b32_e32 v26, v0
	v_mov_b32_e32 v29, v0
	v_max_f32_e32 v236, v182, v183
	v_sub_f32_e32 v236, 0, v236
	v_mov_b32_e32 v237, v236
	v_mov_b32_e32 v238, v236
	v_mov_b32_e32 v239, v236
	v_mov_b32_e32 v240, v236
	v_mov_b32_e32 v241, v236
	v_mov_b32_e32 v242, v236
	v_mov_b32_e32 v243, v236
	v_mov_b32_e32 v244, v236
	v_mov_b32_e32 v245, v236
	v_mov_b32_e32 v246, v236
	v_mov_b32_e32 v247, v236
	v_mov_b32_e32 v248, v236
	v_mov_b32_e32 v249, v236
	v_mov_b32_e32 v250, v236
	v_mov_b32_e32 v251, v236
	s_mov_b32 s98, 0
	s_movk_i32 s99, 0x2400
	s_movk_i32 s100, 0x4800
	s_branch .LBB0_1430
; __device__ __forceinline__ unsigned pk2(float lo, float hi) { f32x2_t v = {lo, hi}; bf16x2_t b = __builtin_convertvector(v, bf16x2_t); return __builtin_bit_cast(unsigned, b); }
; __device__ __forceinline__ float fexp2(float x) { return __builtin_amdgcn_exp2f(x); }
; template <int DQK, int DV>
; __device__ __forceinline__ void attn_pass2(const bf16_t* __restrict__ qh, const bf16_t* __restrict__ kh, const bf16_t* __restrict__ vth, int q0, char* smem, f32x16 (&o)[2][DV / 32], float kmax, int wvp) {
;     ...
;   for (int kt = 0; kt < NT; ++kt) {
;     const int cur = kt & 1;
;     __syncthreads();
;     if (kt + 1 < NT) { STOREKV(cur ^ 1); if (kt + 2 < NT) LOADKV(kt + 2); }
;     f32x16 s[2][2];
;     const char* kb0 = sK + cur * KSB + kofs;
; #pragma unroll
;     for (int ks = 0; ks < NKS; ++ks) {
;       const bf16x8 a0 = *(const bf16x8*)(kb0 + ks * 32), a1 = *(const bf16x8*)(kb0 + 32 * KP + ks * 32);
; #pragma unroll
;       for (int qb = 0; qb < 2; ++qb) {
;         if (ks == 0) {
;           f32x16 z;
; #pragma unroll
;           for (int i = 0; i < 16; ++i) z[i] = 0.f;
;           s[qb][0] = MFMA(a0, qf[qb][0], z); s[qb][1] = MFMA(a1, qf[qb][0], z);
;         } else { s[qb][0] = MFMA(a0, qf[qb][ks], s[qb][0]); s[qb][1] = MFMA(a1, qf[qb][ks], s[qb][1]); }
;       }
;     }
;     __builtin_amdgcn_sched_barrier(0);
; #pragma unroll
;     for (int qb = 0; qb < 2; ++qb) {
;       float rs0 = 0.f, rs1 = 0.f;
; #pragma unroll
;       for (int i = 0; i < 16; ++i) { s[qb][0][i] = fexp2(s[qb][0][i] - mref[qb]); s[qb][1][i] = fexp2(s[qb][1][i] - mref[qb]); rs0 += s[qb][0][i]; rs1 += s[qb][1][i]; }
;       l_run[qb] += rs0 + rs1;
;     }
;     const char* vb0 = sV + cur * VSB + vofs;
; #pragma unroll
;     for (int kb = 0; kb < 2; ++kb)
; #pragma unroll
;       for (int s2 = 0; s2 < 2; ++s2) {
;         bf16x8 pq[2];
; #pragma unroll
;         for (int qb = 0; qb < 2; ++qb) {
;           u32x4 w;
;           w.x = pk2(s[qb][kb][8 * s2 + 0], s[qb][kb][8 * s2 + 1]); w.y = pk2(s[qb][kb][8 * s2 + 2], s[qb][kb][8 * s2 + 3]);
;           w.z = pk2(s[qb][kb][8 * s2 + 4], s[qb][kb][8 * s2 + 5]); w.w = pk2(s[qb][kb][8 * s2 + 6], s[qb][kb][8 * s2 + 7]);
;           pq[qb] = __builtin_bit_cast(bf16x8, w);
;         }
; #pragma unroll
;         for (int eb = 0; eb < NEB; ++eb) {
;           const bf16x8 a = *(const bf16x8*)(vb0 + eb * 32 * VP + (32 * kb + 16 * s2) * 2);
.LBB0_1429:
	s_setprio 1
	s_mulk_i32 s7, 0x2400
	v_add_u32_e32 v180, s7, v169
	ds_read_b128 v[64:67], v180
	ds_read_b128 v[176:179], v180 offset:32
	ds_read_b128 v[68:71], v180 offset:4608
	ds_read_b128 v[192:195], v180 offset:4640
	s_add_i32 s6, s6, 1
	s_waitcnt lgkmcnt(3)
	v_mfma_f32_32x32x16_bf16 v[112:127], v[64:67], v[128:131], v[236:251]
	s_waitcnt lgkmcnt(1)
	v_mfma_f32_32x32x16_bf16 v[96:111], v[68:71], v[128:131], v[236:251]
	v_mfma_f32_32x32x16_bf16 v[80:95], v[64:67], v[144:147], v[236:251]
	v_mfma_f32_32x32x16_bf16 v[64:79], v[68:71], v[144:147], v[236:251]
	v_mfma_f32_32x32x16_bf16 v[112:127], v[176:179], v[132:135], v[112:127]
	s_waitcnt lgkmcnt(0)
	v_mfma_f32_32x32x16_bf16 v[96:111], v[192:195], v[132:135], v[96:111]
	v_mfma_f32_32x32x16_bf16 v[80:95], v[176:179], v[148:151], v[80:95]
	v_mfma_f32_32x32x16_bf16 v[64:79], v[192:195], v[148:151], v[64:79]
	ds_read_b128 v[176:179], v180 offset:64
	ds_read_b128 v[192:195], v180 offset:96
	ds_read_b128 v[196:199], v180 offset:4672
	ds_read_b128 v[200:203], v180 offset:4704
	s_waitcnt lgkmcnt(3)
	v_mfma_f32_32x32x16_bf16 v[112:127], v[176:179], v[136:139], v[112:127]
	s_waitcnt lgkmcnt(1)
	v_mfma_f32_32x32x16_bf16 v[96:111], v[196:199], v[136:139], v[96:111]
	v_mfma_f32_32x32x16_bf16 v[80:95], v[176:179], v[152:155], v[80:95]
	v_mfma_f32_32x32x16_bf16 v[64:79], v[196:199], v[152:155], v[64:79]
	v_mfma_f32_32x32x16_bf16 v[112:127], v[192:195], v[140:143], v[112:127]
	s_waitcnt lgkmcnt(0)
	v_mfma_f32_32x32x16_bf16 v[96:111], v[200:203], v[140:143], v[96:111]
	v_mfma_f32_32x32x16_bf16 v[80:95], v[192:195], v[156:159], v[80:95]
	v_mfma_f32_32x32x16_bf16 v[64:79], v[200:203], v[156:159], v[64:79]
	s_nop 9
	s_setprio 0
	v_exp_f32_e32 v186, v96
	v_exp_f32_e32 v97, v97
	v_exp_f32_e32 v177, v112
	v_exp_f32_e32 v113, v113
	v_exp_f32_e32 v179, v114
	v_exp_f32_e32 v187, v98
	v_add_f32_e32 v98, v97, v186
	v_exp_f32_e32 v115, v115
	v_exp_f32_e32 v190, v99
	v_exp_f32_e32 v204, v100
	v_exp_f32_e32 v99, v116
	v_exp_f32_e32 v117, v117
	v_add_f32_e32 v96, v113, v177
	v_exp_f32_e32 v101, v101
	v_add_f32_e32 v96, v179, v96
	v_exp_f32_e32 v181, v118
	v_add_f32_e32 v96, v115, v96
	v_add_f32_e32 v96, v99, v96
	v_add_f32_e32 v96, v117, v96
	v_add_f32_e32 v112, v181, v96
	v_exp_f32_e32 v176, v119
	v_exp_f32_e32 v178, v103
	v_add_f32_e32 v98, v187, v98
	v_exp_f32_e32 v205, v102
	v_exp_f32_e32 v180, v120
	v_exp_f32_e32 v96, v104
	v_exp_f32_e32 v104, v123
	v_add_f32_e32 v98, v190, v98
	v_exp_f32_e32 v100, v106
	v_exp_f32_e32 v106, v107
	v_add_f32_e32 v98, v204, v98
	v_exp_f32_e32 v118, v124
	v_add_f32_e32 v98, v101, v98
	v_exp_f32_e32 v120, v108
	v_add_f32_e32 v102, v205, v98
	v_exp_f32_e32 v124, v125
	v_exp_f32_e32 v116, v121
	v_exp_f32_e32 v108, v109
	v_exp_f32_e32 v114, v105
	v_exp_f32_e32 v98, v122
	v_exp_f32_e32 v122, v126
	v_exp_f32_e32 v110, v110
	v_exp_f32_e32 v126, v127
	v_exp_f32_e32 v103, v80
	v_exp_f32_e32 v107, v64
	v_exp_f32_e32 v109, v81
	v_exp_f32_e32 v65, v65
	v_exp_f32_e32 v121, v66
	v_add_f32_e32 v66, v109, v103
	v_add_f32_e32 v80, v65, v107
	v_add_f32_e32 v206, v121, v80
	v_exp_f32_e32 v207, v83
	v_add_u32_e32 v209, s98, v185
	v_exp_f32_e32 v64, v111
	v_exp_f32_e32 v111, v82
	v_exp_f32_e32 v208, v84
	ds_read_b128 v[80:83], v209 offset:18432
	ds_read_b128 v[196:199], v209 offset:18464
	ds_read_b128 v[200:203], v209 offset:23040
	v_exp_f32_e32 v212, v85
	v_exp_f32_e32 v213, v86
	v_cvt_pk_bf16_f32 v192, v177, v113
	v_exp_f32_e32 v177, v87
	v_cvt_pk_bf16_f32 v84, v103, v109
	v_exp_f32_e32 v109, v67
	v_add_f32_e32 v66, v111, v66
	v_cvt_pk_bf16_f32 v85, v111, v207
	v_exp_f32_e32 v111, v68
	v_cvt_pk_bf16_f32 v195, v181, v176
	v_exp_f32_e32 v181, v88
	v_cvt_pk_bf16_f32 v194, v99, v117
	v_exp_f32_e32 v117, v89
	v_cvt_pk_bf16_f32 v193, v179, v115
	v_cvt_pk_bf16_f32 v86, v208, v212
	v_cvt_pk_bf16_f32 v87, v213, v177
	v_exp_f32_e32 v99, v90
	s_waitcnt lgkmcnt(2)
	v_mfma_f32_32x32x16_bf16 v[48:63], v[80:83], v[192:195], v[48:63]
	v_exp_f32_e32 v105, v91
	v_exp_f32_e32 v119, v92
	v_exp_f32_e32 v125, v93
	v_mfma_f32_32x32x16_bf16 v[16:31], v[80:83], v[84:87], v[16:31]
	ds_read_b128 v[80:83], v209 offset:23072
	v_exp_f32_e32 v123, v94
	v_exp_f32_e32 v92, v69
	v_exp_f32_e32 v127, v95
	s_waitcnt lgkmcnt(1)
	v_mfma_f32_32x32x16_bf16 v[0:15], v[200:203], v[84:87], v[0:15]
	v_exp_f32_e32 v93, v70
	v_add_f32_e32 v66, v207, v66
	v_add_f32_e32 v67, v109, v206
	v_add_f32_e32 v66, v208, v66
	v_add_f32_e32 v67, v111, v67
	v_add_f32_e32 v66, v212, v66
	v_add_f32_e32 v67, v92, v67
	v_mfma_f32_32x32x16_bf16 v[32:47], v[200:203], v[192:195], v[32:47]
	v_cvt_pk_bf16_f32 v84, v180, v116
	v_cvt_pk_bf16_f32 v85, v98, v104
	v_cvt_pk_bf16_f32 v86, v118, v124
	v_cvt_pk_bf16_f32 v87, v122, v126
	v_cvt_pk_bf16_f32 v88, v181, v117
	v_cvt_pk_bf16_f32 v89, v99, v105
	v_cvt_pk_bf16_f32 v90, v119, v125
	v_cvt_pk_bf16_f32 v91, v123, v127
	v_add_f32_e32 v113, v213, v66
	v_add_f32_e32 v103, v93, v67
	ds_read_b128 v[66:69], v209 offset:18496
	v_mfma_f32_32x32x16_bf16 v[48:63], v[196:199], v[84:87], v[48:63]
	v_exp_f32_e32 v179, v71
	v_mov_b32_e32 v70, v72
	v_exp_f32_e32 v115, v73
	v_cvt_pk_bf16_f32 v71, v121, v109
	v_cvt_pk_bf16_f32 v72, v111, v92
	v_cvt_pk_bf16_f32 v73, v93, v179
	v_mfma_f32_32x32x16_bf16 v[16:31], v[196:199], v[88:91], v[16:31]
	s_waitcnt lgkmcnt(1)
	v_mfma_f32_32x32x16_bf16 v[0:15], v[80:83], v[88:91], v[0:15]
	ds_read_b128 v[88:91], v209 offset:23104
	v_mfma_f32_32x32x16_bf16 v[32:47], v[80:83], v[84:87], v[32:47]
	v_cvt_pk_bf16_f32 v80, v186, v97
	v_exp_f32_e32 v97, v70
	v_cvt_pk_bf16_f32 v70, v107, v65
	v_cvt_pk_bf16_f32 v81, v187, v190
	v_cvt_pk_bf16_f32 v82, v204, v101
	v_cvt_pk_bf16_f32 v83, v205, v178
	v_exp_f32_e32 v101, v74
	ds_read_b128 v[84:87], v209 offset:18528
	s_waitcnt lgkmcnt(2)
; __device__ __forceinline__ unsigned pk2(float lo, float hi) { f32x2_t v = {lo, hi}; bf16x2_t b = __builtin_convertvector(v, bf16x2_t); return __builtin_bit_cast(unsigned, b); }
; __device__ __forceinline__ float fexp2(float x) { return __builtin_amdgcn_exp2f(x); }
; #define MFMA(a, b, c) __builtin_amdgcn_mfma_f32_32x32x16_bf16((a), (b), (c), 0, 0, 0)
; #define LOADKV(t) do { \
;     _Pragma("unroll") for (int j = 0; j < NKC; ++j) if (j + 1 < NKC || k1) rk[j] = *(const u32x4*)(kh + (size_t)(t) * 64 * DQK + (size_t)(tid + 512 * j) * 8); \
;     _Pragma("unroll") for (int j = 0; j < NVC; ++j) rv[j] = *(const u32x4*)(vg0 + (size_t)(64 * j) * S + (size_t)(t) * 64); } while (0)
; template <int DQK, int DV>
; __device__ __forceinline__ void attn_pass2(const bf16_t* __restrict__ qh, const bf16_t* __restrict__ kh, const bf16_t* __restrict__ vth, int q0, char* smem, f32x16 (&o)[2][DV / 32], float kmax, int wvp) {
;     ...
; #pragma unroll 1
;   for (int kt = 0; kt < NT; ++kt) {
;     const int cur = kt & 1;
;     __syncthreads();
;     if (kt + 1 < NT) { STOREKV(cur ^ 1); if (kt + 2 < NT) LOADKV(kt + 2); }
;     ...
;     for (int qb = 0; qb < 2; ++qb) {
;       float rs0 = 0.f, rs1 = 0.f;
; #pragma unroll
;       for (int i = 0; i < 16; ++i) { s[qb][0][i] = fexp2(s[qb][0][i] - mref[qb]); s[qb][1][i] = fexp2(s[qb][1][i] - mref[qb]); rs0 += s[qb][0][i]; rs1 += s[qb][1][i]; }
;       l_run[qb] += rs0 + rs1;
;     }
;     const char* vb0 = sV + cur * VSB + vofs;
; #pragma unroll
;     for (int kb = 0; kb < 2; ++kb)
; #pragma unroll
;       for (int s2 = 0; s2 < 2; ++s2) {
;         bf16x8 pq[2];
; #pragma unroll
;         for (int qb = 0; qb < 2; ++qb) {
;           u32x4 w;
;           w.x = pk2(s[qb][kb][8 * s2 + 0], s[qb][kb][8 * s2 + 1]); w.y = pk2(s[qb][kb][8 * s2 + 2], s[qb][kb][8 * s2 + 3]);
;           w.z = pk2(s[qb][kb][8 * s2 + 4], s[qb][kb][8 * s2 + 5]); w.w = pk2(s[qb][kb][8 * s2 + 6], s[qb][kb][8 * s2 + 7]);
;           pq[qb] = __builtin_bit_cast(bf16x8, w);
;         }
; #pragma unroll
;         for (int eb = 0; eb < NEB; ++eb) {
;           const bf16x8 a = *(const bf16x8*)(vb0 + eb * 32 * VP + (32 * kb + 16 * s2) * 2);
; #pragma unroll
;           for (int qb = 0; qb < 2; ++qb) o[qb][eb] = MFMA(a, pq[qb], o[qb][eb]);
;         }
;       }
;   }
	v_mfma_f32_32x32x16_bf16 v[48:63], v[66:69], v[80:83], v[48:63]
	v_exp_f32_e32 v107, v75
	v_exp_f32_e32 v121, v76
	v_exp_f32_e32 v109, v77
	v_exp_f32_e32 v111, v78
	v_mfma_f32_32x32x16_bf16 v[16:31], v[66:69], v[70:73], v[16:31]
	ds_read_b128 v[66:69], v209 offset:23136
	v_exp_f32_e32 v65, v79
	v_add_f32_e32 v74, v178, v102
	v_add_f32_e32 v75, v179, v103
	s_nop 0
	v_add_f32_e32 v74, v96, v74
	v_add_f32_e32 v75, v97, v75
	s_waitcnt lgkmcnt(2)
	v_mfma_f32_32x32x16_bf16 v[32:47], v[88:91], v[80:83], v[32:47]
	v_add_f32_e64 v80, v114, v74
	v_add_f32_e64 v81, v115, v75
	v_cvt_pk_bf16_f32 v74, v97, v115
	v_cvt_pk_bf16_f32 v75, v101, v107
	v_add_f32_e64 v80, v100, v80
	v_add_f32_e64 v81, v101, v81
	v_add_f32_e32 v80, v106, v80
	v_add_f32_e32 v81, v107, v81
	v_mfma_f32_32x32x16_bf16 v[0:15], v[88:91], v[70:73], v[0:15]
	v_add_f32_e64 v70, v176, v112
	v_add_f32_e64 v71, v177, v113
	v_cvt_pk_bf16_f32 v72, v120, v108
	v_add_f32_e64 v76, v180, v70
	v_add_f32_e64 v77, v181, v71
	v_cvt_pk_bf16_f32 v70, v96, v114
	v_cvt_pk_bf16_f32 v71, v100, v106
	v_cvt_pk_bf16_f32 v73, v110, v64
	v_add_f32_e32 v78, v116, v76
	v_add_f32_e32 v79, v117, v77
	v_cvt_pk_bf16_f32 v76, v121, v109
	v_cvt_pk_bf16_f32 v77, v111, v65
	s_waitcnt lgkmcnt(1)
	v_mfma_f32_32x32x16_bf16 v[48:63], v[84:87], v[70:73], v[48:63]
	v_add_f32_e64 v78, v98, v78
	v_add_f32_e64 v79, v99, v79
	v_add_f32_e64 v80, v120, v80
	v_add_f32_e64 v81, v121, v81
	v_add_f32_e64 v78, v104, v78
	v_add_f32_e64 v79, v105, v79
	v_add_f32_e32 v78, v118, v78
	v_add_f32_e32 v79, v119, v79
	s_nop 0
	v_add_f32_e32 v78, v124, v78
	v_add_f32_e32 v79, v125, v79
	v_mfma_f32_32x32x16_bf16 v[16:31], v[84:87], v[74:77], v[16:31]
	s_waitcnt lgkmcnt(0)
	v_mfma_f32_32x32x16_bf16 v[32:47], v[66:69], v[70:73], v[32:47]
	v_add_f32_e64 v70, v108, v80
	v_add_f32_e64 v71, v109, v81
	v_add_f32_e64 v72, v122, v78
	v_add_f32_e64 v73, v123, v79
	v_add_f32_e64 v70, v110, v70
	v_add_f32_e64 v71, v111, v71
	v_add_f32_e32 v72, v126, v72
	v_add_f32_e32 v73, v127, v73
	v_add_f32_e32 v64, v64, v70
	v_add_f32_e32 v65, v65, v71
	s_nop 0
	v_add_f32_e32 v64, v72, v64
	v_add_f32_e32 v65, v73, v65
	v_mfma_f32_32x32x16_bf16 v[0:15], v[66:69], v[74:77], v[0:15]
	v_add_f32_e64 v174, v174, v64
	v_add_f32_e64 v175, v175, v65
	s_mov_b32 s101, s100
	s_mov_b32 s100, s98
	s_mov_b32 s98, s99
	s_mov_b32 s99, s101
	s_cmpk_lg_i32 s6, 0x80
	s_cbranch_scc0 .LBB0_1433
.LBB0_1430:
	s_and_b32 s7, s6, 1
	s_cmpk_eq_i32 s6, 0x7f
	s_waitcnt lgkmcnt(0)
	s_barrier
	s_cbranch_scc1 .Lgqa_top_done
	s_xor_b32 s8, s7, 1
	s_mulk_i32 s8, 0x2400
	v_add_u32_e32 v214, s8, v184
	s_waitcnt vmcnt(1)
	ds_write_b128 v214, v[160:163]
	v_add_u32_e32 v214, s99, v168
	s_cmpk_gt_u32 s6, 0x7d
	s_waitcnt vmcnt(0)
	ds_write_b128 v214, v[164:167] offset:18432
	s_cbranch_scc1 .Lgqa_top_done
	global_load_dwordx4 v[160:163], v[170:171], off
	global_load_dwordx4 v[164:167], v[172:173], off
	v_lshl_add_u64 v[170:171], v[170:171], 0, s[52:53]
	v_lshl_add_u64 v[172:173], v[172:173], 0, s[54:55]
.Lgqa_top_done:
	s_cmp_lt_u32 s27, 0x100
	s_cbranch_scc1 .LBB0_1429
	s_cmp_eq_u32 s6, 0
	s_cbranch_scc1 .Lgqa_rot_qk
.Lgqa_rot_exp:
	s_setprio 0
	v_exp_f32_e32 v186, v96
	v_exp_f32_e32 v97, v97
	v_exp_f32_e32 v177, v112
	v_exp_f32_e32 v113, v113
	v_exp_f32_e32 v179, v114
	v_exp_f32_e32 v187, v98
	v_add_f32_e32 v98, v97, v186
	v_exp_f32_e32 v115, v115
	v_exp_f32_e32 v190, v99
	v_exp_f32_e32 v204, v100
	v_exp_f32_e32 v99, v116
	v_exp_f32_e32 v117, v117
	v_add_f32_e32 v96, v113, v177
	v_exp_f32_e32 v101, v101
	v_add_f32_e32 v96, v179, v96
	v_exp_f32_e32 v181, v118
	v_add_f32_e32 v96, v115, v96
	v_add_f32_e32 v96, v99, v96
	v_add_f32_e32 v96, v117, v96
	v_add_f32_e32 v112, v181, v96
	v_exp_f32_e32 v176, v119
	v_exp_f32_e32 v178, v103
	v_add_f32_e32 v98, v187, v98
	v_exp_f32_e32 v205, v102
	v_exp_f32_e32 v180, v120
	v_exp_f32_e32 v96, v104
	v_exp_f32_e32 v104, v123
	v_add_f32_e32 v98, v190, v98
	v_exp_f32_e32 v100, v106
	v_exp_f32_e32 v106, v107
	v_add_f32_e32 v98, v204, v98
	v_exp_f32_e32 v118, v124
	v_add_f32_e32 v98, v101, v98
	v_exp_f32_e32 v120, v108
	v_add_f32_e32 v102, v205, v98
	v_exp_f32_e32 v124, v125
	v_exp_f32_e32 v116, v121
	v_exp_f32_e32 v108, v109
	v_exp_f32_e32 v114, v105
	v_exp_f32_e32 v98, v122
	v_exp_f32_e32 v122, v126
	v_exp_f32_e32 v110, v110
	v_exp_f32_e32 v126, v127
	v_exp_f32_e32 v103, v80
	v_exp_f32_e32 v107, v64
	v_exp_f32_e32 v109, v81
	v_exp_f32_e32 v65, v65
	v_exp_f32_e32 v121, v66
	v_add_f32_e32 v66, v109, v103
	v_add_f32_e32 v80, v65, v107
	v_add_f32_e32 v206, v121, v80
	v_exp_f32_e32 v207, v83
	v_add_u32_e32 v209, s100, v185
	v_exp_f32_e32 v64, v111
	v_exp_f32_e32 v111, v82
	v_exp_f32_e32 v208, v84
	ds_read_b128 v[80:83], v209 offset:18432
	ds_read_b128 v[196:199], v209 offset:18464
	ds_read_b128 v[200:203], v209 offset:23040
	v_exp_f32_e32 v212, v85
	v_exp_f32_e32 v213, v86
	v_cvt_pk_bf16_f32 v192, v177, v113
	v_exp_f32_e32 v177, v87
	v_cvt_pk_bf16_f32 v84, v103, v109
	v_exp_f32_e32 v109, v67
	v_add_f32_e32 v66, v111, v66
	v_cvt_pk_bf16_f32 v85, v111, v207
	v_exp_f32_e32 v111, v68
	v_cvt_pk_bf16_f32 v195, v181, v176
	v_exp_f32_e32 v181, v88
	v_cvt_pk_bf16_f32 v194, v99, v117
	v_exp_f32_e32 v117, v89
	v_cvt_pk_bf16_f32 v193, v179, v115
	v_cvt_pk_bf16_f32 v86, v208, v212
	v_cvt_pk_bf16_f32 v87, v213, v177
	v_exp_f32_e32 v99, v90
	s_waitcnt lgkmcnt(2)
	v_mfma_f32_32x32x16_bf16 v[48:63], v[80:83], v[192:195], v[48:63]
	v_exp_f32_e32 v105, v91
	v_exp_f32_e32 v119, v92
	v_exp_f32_e32 v125, v93
	v_mfma_f32_32x32x16_bf16 v[16:31], v[80:83], v[84:87], v[16:31]
	ds_read_b128 v[80:83], v209 offset:23072
	v_exp_f32_e32 v123, v94
	v_exp_f32_e32 v92, v69
	v_exp_f32_e32 v127, v95
	s_waitcnt lgkmcnt(1)
; __device__ __forceinline__ unsigned pk2(float lo, float hi) { f32x2_t v = {lo, hi}; bf16x2_t b = __builtin_convertvector(v, bf16x2_t); return __builtin_bit_cast(unsigned, b); }
; #define MFMA(a, b, c) __builtin_amdgcn_mfma_f32_32x32x16_bf16((a), (b), (c), 0, 0, 0)
; template <int DQK, int DV>
; __device__ __forceinline__ void attn_pass2(const bf16_t* __restrict__ qh, const bf16_t* __restrict__ kh, const bf16_t* __restrict__ vth, int q0, char* smem, f32x16 (&o)[2][DV / 32], float kmax, int wvp) {
;     ...
;     const char* kb0 = sK + cur * KSB + kofs;
; #pragma unroll
;     for (int ks = 0; ks < NKS; ++ks) {
;       const bf16x8 a0 = *(const bf16x8*)(kb0 + ks * 32), a1 = *(const bf16x8*)(kb0 + 32 * KP + ks * 32);
; #pragma unroll
;       for (int qb = 0; qb < 2; ++qb) {
;         if (ks == 0) {
;           f32x16 z;
; #pragma unroll
;           for (int i = 0; i < 16; ++i) z[i] = 0.f;
;           s[qb][0] = MFMA(a0, qf[qb][0], z); s[qb][1] = MFMA(a1, qf[qb][0], z);
;         } else { s[qb][0] = MFMA(a0, qf[qb][ks], s[qb][0]); s[qb][1] = MFMA(a1, qf[qb][ks], s[qb][1]); }
;       }
;     }
;     ...
;     const char* vb0 = sV + cur * VSB + vofs;
; #pragma unroll
;     for (int kb = 0; kb < 2; ++kb)
; #pragma unroll
;       for (int s2 = 0; s2 < 2; ++s2) {
;         bf16x8 pq[2];
; #pragma unroll
;         for (int qb = 0; qb < 2; ++qb) {
;           u32x4 w;
;           w.x = pk2(s[qb][kb][8 * s2 + 0], s[qb][kb][8 * s2 + 1]); w.y = pk2(s[qb][kb][8 * s2 + 2], s[qb][kb][8 * s2 + 3]);
;           w.z = pk2(s[qb][kb][8 * s2 + 4], s[qb][kb][8 * s2 + 5]); w.w = pk2(s[qb][kb][8 * s2 + 6], s[qb][kb][8 * s2 + 7]);
;           pq[qb] = __builtin_bit_cast(bf16x8, w);
;         }
; #pragma unroll
;         for (int eb = 0; eb < NEB; ++eb) {
;           const bf16x8 a = *(const bf16x8*)(vb0 + eb * 32 * VP + (32 * kb + 16 * s2) * 2);
; #pragma unroll
;           for (int qb = 0; qb < 2; ++qb) o[qb][eb] = MFMA(a, pq[qb], o[qb][eb]);
;         }
;       }
;   }
	v_mfma_f32_32x32x16_bf16 v[0:15], v[200:203], v[84:87], v[0:15]
	v_exp_f32_e32 v93, v70
	v_add_f32_e32 v66, v207, v66
	v_add_f32_e32 v67, v109, v206
	v_add_f32_e32 v66, v208, v66
	v_add_f32_e32 v67, v111, v67
	v_add_f32_e32 v66, v212, v66
	v_add_f32_e32 v67, v92, v67
	v_mfma_f32_32x32x16_bf16 v[32:47], v[200:203], v[192:195], v[32:47]
	v_cvt_pk_bf16_f32 v84, v180, v116
	v_cvt_pk_bf16_f32 v85, v98, v104
	v_cvt_pk_bf16_f32 v86, v118, v124
	v_cvt_pk_bf16_f32 v87, v122, v126
	v_cvt_pk_bf16_f32 v88, v181, v117
	v_cvt_pk_bf16_f32 v89, v99, v105
	v_cvt_pk_bf16_f32 v90, v119, v125
	v_cvt_pk_bf16_f32 v91, v123, v127
	v_add_f32_e32 v113, v213, v66
	v_add_f32_e32 v103, v93, v67
	ds_read_b128 v[66:69], v209 offset:18496
	v_mfma_f32_32x32x16_bf16 v[48:63], v[196:199], v[84:87], v[48:63]
	v_exp_f32_e32 v179, v71
	v_mov_b32_e32 v70, v72
	v_exp_f32_e32 v115, v73
	v_cvt_pk_bf16_f32 v71, v121, v109
	v_cvt_pk_bf16_f32 v72, v111, v92
	v_cvt_pk_bf16_f32 v73, v93, v179
	v_mfma_f32_32x32x16_bf16 v[16:31], v[196:199], v[88:91], v[16:31]
	s_waitcnt lgkmcnt(1)
	v_mfma_f32_32x32x16_bf16 v[0:15], v[80:83], v[88:91], v[0:15]
	ds_read_b128 v[88:91], v209 offset:23104
	v_mfma_f32_32x32x16_bf16 v[32:47], v[80:83], v[84:87], v[32:47]
	v_cvt_pk_bf16_f32 v80, v186, v97
	v_exp_f32_e32 v97, v70
	v_cvt_pk_bf16_f32 v70, v107, v65
	v_cvt_pk_bf16_f32 v81, v187, v190
	v_cvt_pk_bf16_f32 v82, v204, v101
	v_cvt_pk_bf16_f32 v83, v205, v178
	v_exp_f32_e32 v101, v74
	ds_read_b128 v[84:87], v209 offset:18528
	s_waitcnt lgkmcnt(2)
	v_mfma_f32_32x32x16_bf16 v[48:63], v[66:69], v[80:83], v[48:63]
	v_exp_f32_e32 v107, v75
	v_exp_f32_e32 v121, v76
	v_exp_f32_e32 v109, v77
	v_exp_f32_e32 v111, v78
	v_mfma_f32_32x32x16_bf16 v[16:31], v[66:69], v[70:73], v[16:31]
	ds_read_b128 v[66:69], v209 offset:23136
	v_exp_f32_e32 v65, v79
	v_add_f32_e32 v74, v178, v102
	v_add_f32_e32 v75, v179, v103
	s_nop 0
	v_add_f32_e32 v74, v96, v74
	v_add_f32_e32 v75, v97, v75
	s_waitcnt lgkmcnt(2)
	v_mfma_f32_32x32x16_bf16 v[32:47], v[88:91], v[80:83], v[32:47]
	v_add_f32_e64 v80, v114, v74
	v_add_f32_e64 v81, v115, v75
	v_cvt_pk_bf16_f32 v74, v97, v115
	v_cvt_pk_bf16_f32 v75, v101, v107
	v_add_f32_e64 v80, v100, v80
	v_add_f32_e64 v81, v101, v81
	v_add_f32_e32 v80, v106, v80
	v_add_f32_e32 v81, v107, v81
	v_mfma_f32_32x32x16_bf16 v[0:15], v[88:91], v[70:73], v[0:15]
	v_add_f32_e64 v70, v176, v112
	v_add_f32_e64 v71, v177, v113
	v_cvt_pk_bf16_f32 v72, v120, v108
	v_add_f32_e64 v76, v180, v70
	v_add_f32_e64 v77, v181, v71
	v_cvt_pk_bf16_f32 v70, v96, v114
	v_cvt_pk_bf16_f32 v71, v100, v106
	v_cvt_pk_bf16_f32 v73, v110, v64
	v_add_f32_e32 v78, v116, v76
	v_add_f32_e32 v79, v117, v77
	v_cvt_pk_bf16_f32 v76, v121, v109
	v_cvt_pk_bf16_f32 v77, v111, v65
	s_waitcnt lgkmcnt(1)
	v_mfma_f32_32x32x16_bf16 v[48:63], v[84:87], v[70:73], v[48:63]
	v_add_f32_e64 v78, v98, v78
	v_add_f32_e64 v79, v99, v79
	v_add_f32_e64 v80, v120, v80
	v_add_f32_e64 v81, v121, v81
	v_add_f32_e64 v78, v104, v78
	v_add_f32_e64 v79, v105, v79
	v_add_f32_e32 v78, v118, v78
	v_add_f32_e32 v79, v119, v79
	s_nop 0
	v_add_f32_e32 v78, v124, v78
	v_add_f32_e32 v79, v125, v79
	v_mfma_f32_32x32x16_bf16 v[16:31], v[84:87], v[74:77], v[16:31]
	s_waitcnt lgkmcnt(0)
	v_mfma_f32_32x32x16_bf16 v[32:47], v[66:69], v[70:73], v[32:47]
	v_add_f32_e64 v70, v108, v80
	v_add_f32_e64 v71, v109, v81
	v_add_f32_e64 v72, v122, v78
	v_add_f32_e64 v73, v123, v79
	v_add_f32_e64 v70, v110, v70
	v_add_f32_e64 v71, v111, v71
	v_add_f32_e32 v72, v126, v72
	v_add_f32_e32 v73, v127, v73
	v_add_f32_e32 v64, v64, v70
	v_add_f32_e32 v65, v65, v71
	s_nop 0
	v_add_f32_e32 v64, v72, v64
	v_add_f32_e32 v65, v73, v65
	v_mfma_f32_32x32x16_bf16 v[0:15], v[66:69], v[74:77], v[0:15]
	v_add_f32_e64 v174, v174, v64
	v_add_f32_e64 v175, v175, v65
	s_cmpk_eq_i32 s6, 0x80
	s_cbranch_scc1 .LBB0_1433
.Lgqa_rot_qk:
	s_setprio 1
	s_mulk_i32 s7, 0x2400
	v_add_u32_e32 v180, s7, v169
	ds_read_b128 v[64:67], v180
	ds_read_b128 v[176:179], v180 offset:32
	ds_read_b128 v[68:71], v180 offset:4608
	ds_read_b128 v[192:195], v180 offset:4640
	s_add_i32 s6, s6, 1
	s_waitcnt lgkmcnt(3)
	v_mfma_f32_32x32x16_bf16 v[112:127], v[64:67], v[128:131], v[236:251]
	s_waitcnt lgkmcnt(1)
	v_mfma_f32_32x32x16_bf16 v[96:111], v[68:71], v[128:131], v[236:251]
	v_mfma_f32_32x32x16_bf16 v[80:95], v[64:67], v[144:147], v[236:251]
	v_mfma_f32_32x32x16_bf16 v[64:79], v[68:71], v[144:147], v[236:251]
	v_mfma_f32_32x32x16_bf16 v[112:127], v[176:179], v[132:135], v[112:127]
	s_waitcnt lgkmcnt(0)
	v_mfma_f32_32x32x16_bf16 v[96:111], v[192:195], v[132:135], v[96:111]
	v_mfma_f32_32x32x16_bf16 v[80:95], v[176:179], v[148:151], v[80:95]
	v_mfma_f32_32x32x16_bf16 v[64:79], v[192:195], v[148:151], v[64:79]
	ds_read_b128 v[176:179], v180 offset:64
	ds_read_b128 v[192:195], v180 offset:96
	ds_read_b128 v[196:199], v180 offset:4672
	ds_read_b128 v[200:203], v180 offset:4704
	s_waitcnt lgkmcnt(3)
	v_mfma_f32_32x32x16_bf16 v[112:127], v[176:179], v[136:139], v[112:127]
	s_waitcnt lgkmcnt(1)
	v_mfma_f32_32x32x16_bf16 v[96:111], v[196:199], v[136:139], v[96:111]
	v_mfma_f32_32x32x16_bf16 v[80:95], v[176:179], v[152:155], v[80:95]
	v_mfma_f32_32x32x16_bf16 v[64:79], v[196:199], v[152:155], v[64:79]
	v_mfma_f32_32x32x16_bf16 v[112:127], v[192:195], v[140:143], v[112:127]
	s_waitcnt lgkmcnt(0)
	v_mfma_f32_32x32x16_bf16 v[96:111], v[200:203], v[140:143], v[96:111]
	v_mfma_f32_32x32x16_bf16 v[80:95], v[192:195], v[156:159], v[80:95]
	v_mfma_f32_32x32x16_bf16 v[64:79], v[200:203], v[156:159], v[64:79]
	s_mov_b32 s101, s100
	s_mov_b32 s100, s98
	s_mov_b32 s98, s99
	s_mov_b32 s99, s101
	s_cmpk_lg_i32 s6, 0x80
	s_cbranch_scc1 .LBB0_1430
	s_nop 5
	s_branch .Lgqa_rot_exp

; __global__ void __launch_bounds__(512, 2) mega_fwd(Params p_arg) {
;   typedef const __attribute__((address_space(4))) Params* KParamsPtr;
;   KParamsPtr pptr = (KParamsPtr)__builtin_amdgcn_kernarg_segment_ptr(); asm volatile("" : "+s"(pptr));
;   const __attribute__((address_space(4))) Params& p = *pptr;
;   __shared__ __attribute__((aligned(16))) char smem[147456 + 16];
	.amdhsa_kernel _Z8mega_fwd6Params
		.amdhsa_group_segment_fixed_size 147472
		.amdhsa_private_segment_fixed_size 0
		.amdhsa_kernarg_size 528
		.amdhsa_user_sgpr_count 2
		.amdhsa_user_sgpr_dispatch_ptr 0
		.amdhsa_user_sgpr_queue_ptr 0
		.amdhsa_user_sgpr_kernarg_segment_ptr 1
		.amdhsa_user_sgpr_dispatch_id 0
		.amdhsa_user_sgpr_kernarg_preload_length 0
		.amdhsa_user_sgpr_kernarg_preload_offset 0
		.amdhsa_user_sgpr_private_segment_size 0
		.amdhsa_uses_dynamic_stack 0
		.amdhsa_enable_private_segment 0
		.amdhsa_system_sgpr_workgroup_id_x 1
		.amdhsa_system_sgpr_workgroup_id_y 0
		.amdhsa_system_sgpr_workgroup_id_z 0
		.amdhsa_system_sgpr_workgroup_info 0
		.amdhsa_system_vgpr_workitem_id 2
		.amdhsa_next_free_vgpr 253
		.amdhsa_next_free_sgpr 102
		.amdhsa_accum_offset 256
		.amdhsa_reserve_vcc 1
		.amdhsa_float_round_mode_32 0
		.amdhsa_float_round_mode_16_64 0
		.amdhsa_float_denorm_mode_32 3
		.amdhsa_float_denorm_mode_16_64 3
		.amdhsa_dx10_clamp 1
		.amdhsa_ieee_mode 1
		.amdhsa_fp16_overflow 0
		.amdhsa_tg_split 0
		.amdhsa_exception_fp_ieee_invalid_op 0
		.amdhsa_exception_fp_denorm_src 0
		.amdhsa_exception_fp_ieee_div_zero 0
		.amdhsa_exception_fp_ieee_overflow 0
		.amdhsa_exception_fp_ieee_underflow 0
		.amdhsa_exception_fp_ieee_inexact 0
		.amdhsa_exception_int_div_zero 0
	.end_amdhsa_kernel

; __global__ void __launch_bounds__(512, 2) mega_fwd(Params p_arg) {
;   typedef const __attribute__((address_space(4))) Params* KParamsPtr;
;   KParamsPtr pptr = (KParamsPtr)__builtin_amdgcn_kernarg_segment_ptr(); asm volatile("" : "+s"(pptr));
;   const __attribute__((address_space(4))) Params& p = *pptr;
;   __shared__ __attribute__((aligned(16))) char smem[147456 + 16];
amdhsa.kernels:
  - .agpr_count:     0
    .args:
      - .offset:         0
        .size:           272
        .value_kind:     by_value
      - .offset:         272
        .size:           4
        .value_kind:     hidden_block_count_x
      - .offset:         276
        .size:           4
        .value_kind:     hidden_block_count_y
      - .offset:         280
        .size:           4
        .value_kind:     hidden_block_count_z
      - .offset:         284
        .size:           2
        .value_kind:     hidden_group_size_x
      - .offset:         286
        .size:           2
        .value_kind:     hidden_group_size_y
      - .offset:         288
        .size:           2
        .value_kind:     hidden_group_size_z
      - .offset:         290
        .size:           2
        .value_kind:     hidden_remainder_x
      - .offset:         292
        .size:           2
        .value_kind:     hidden_remainder_y
      - .offset:         294
        .size:           2
        .value_kind:     hidden_remainder_z
      - .offset:         312
        .size:           8
        .value_kind:     hidden_global_offset_x
      - .offset:         320
        .size:           8
        .value_kind:     hidden_global_offset_y
      - .offset:         328
        .size:           8
        .value_kind:     hidden_global_offset_z
      - .offset:         336
        .size:           2
        .value_kind:     hidden_grid_dims
      - .offset:         360
        .size:           8
        .value_kind:     hidden_multigrid_sync_arg
    .group_segment_fixed_size: 147472
    .kernarg_segment_align: 8
    .kernarg_segment_size: 528
    .language:       OpenCL C
    .language_version:
      - 2
      - 0
    .max_flat_workgroup_size: 512
    .name:           _Z8mega_fwd6Params
    .private_segment_fixed_size: 0
    .sgpr_count:     108
    .sgpr_spill_count: 35
    .symbol:         _Z8mega_fwd6Params.kd
    .uniform_work_group_size: 1
    .uses_dynamic_stack: false
    .vgpr_count:     253
    .vgpr_spill_count: 0
    .wavefront_size: 64
